# v030: v026 + two store-completion waits removed (attention pass head, 3-item SGU loop head)
# baseline (speedup 1.0000x reference)
.LBB0_41:
	v_cndmask_b32_e64 v0, 0, 1, s[12:13]
	s_cmp_eq_u32 s0, s21
	v_cmp_ne_u32_e64 s[0:1], 1, v0
	s_mov_b64 s[4:5], -1
	s_cbranch_scc1 .LBB0_44
	v_readlane_b32 s48, v250, 31
	s_and_b64 vcc, exec, s[0:1]
	s_mov_b32 s23, s22
	s_mov_b32 s25, s20
	v_readlane_b32 s58, v250, 41
	v_readlane_b32 s59, v250, 42
	v_readlane_b32 s49, v250, 32
	v_readlane_b32 s50, v250, 33
	v_readlane_b32 s51, v250, 34
	v_readlane_b32 s52, v250, 35
	v_readlane_b32 s53, v250, 36
	v_readlane_b32 s54, v250, 37
	v_readlane_b32 s55, v250, 38
	v_readlane_b32 s56, v250, 39
	v_readlane_b32 s57, v250, 40
	v_readlane_b32 s60, v250, 43
	v_readlane_b32 s61, v250, 44
	v_readlane_b32 s62, v250, 45
	v_readlane_b32 s63, v250, 46
	s_cbranch_vccz .LBB0_50

.LBB0_122:
	s_add_i32 s12, s7, s8
	v_mov_b32_e32 v65, v214
	s_lshl_b32 s0, s12, 5
	v_readfirstlane_b32 s11, v65
	s_ashr_i32 s13, s11, 6
	s_and_b32 s9, s0, 0xffffff80
	s_mov_b64 s[0:1], s[42:43]
	s_add_u32 s4, s0, 0x18400000
	s_addc_u32 s5, s1, 0
	s_lshl_b32 s10, s13, 4
	s_add_i32 s0, s10, s9
	s_mul_i32 s14, s0, 0x3800
	v_and_b32_e32 v178, 63, v65
	s_mul_hi_i32 s1, s0, 0x3800
	s_add_u32 s14, s4, s14
	s_addc_u32 s15, s5, s1
	v_lshlrev_b32_e32 v192, 4, v178
	s_or_b32 s1, s0, 1
	v_lshl_add_u64 v[0:1], s[14:15], 0, v[192:193]
	s_mul_hi_i32 s15, s1, 0x3800
	s_mulk_i32 s1, 0x3800
	s_add_u32 s14, s4, s1
	s_addc_u32 s15, s5, s15
	s_or_b32 s1, s0, 2
	v_add_co_u32_e32 v0, vcc, s65, v0
	v_lshl_add_u64 v[2:3], s[14:15], 0, v[192:193]
	s_mul_hi_i32 s15, s1, 0x3800
	s_mulk_i32 s1, 0x3800
	v_addc_co_u32_e32 v1, vcc, 0, v1, vcc
	s_add_u32 s14, s4, s1
	v_add_co_u32_e32 v2, vcc, s65, v2
	s_addc_u32 s15, s5, s15
	s_or_b32 s1, s0, 3
	v_addc_co_u32_e32 v3, vcc, 0, v3, vcc
	global_load_dwordx4 v[48:51], v[0:1], off
	global_load_dwordx4 v[52:55], v[2:3], off
	v_lshl_add_u64 v[0:1], s[14:15], 0, v[192:193]
	s_mul_hi_i32 s15, s1, 0x3800
	s_mulk_i32 s1, 0x3800
	s_add_u32 s14, s4, s1
	s_addc_u32 s15, s5, s15
	s_or_b32 s1, s0, 4
	v_add_co_u32_e32 v0, vcc, s65, v0
	v_lshl_add_u64 v[2:3], s[14:15], 0, v[192:193]
	s_mul_hi_i32 s15, s1, 0x3800
	s_mulk_i32 s1, 0x3800
	v_addc_co_u32_e32 v1, vcc, 0, v1, vcc
	s_add_u32 s14, s4, s1
	v_add_co_u32_e32 v2, vcc, s65, v2
	s_addc_u32 s15, s5, s15
	s_or_b32 s1, s0, 5
	v_addc_co_u32_e32 v3, vcc, 0, v3, vcc
	global_load_dwordx4 v[56:59], v[0:1], off
	global_load_dwordx4 v[60:63], v[2:3], off
	v_lshl_add_u64 v[0:1], s[14:15], 0, v[192:193]
	s_mul_hi_i32 s15, s1, 0x3800
	s_mulk_i32 s1, 0x3800
	s_add_u32 s14, s4, s1
	s_addc_u32 s15, s5, s15
	s_or_b32 s1, s0, 6
	v_add_co_u32_e32 v0, vcc, s65, v0
	v_lshl_add_u64 v[2:3], s[14:15], 0, v[192:193]
	s_mul_hi_i32 s15, s1, 0x3800
	s_mulk_i32 s1, 0x3800
	v_addc_co_u32_e32 v1, vcc, 0, v1, vcc
	s_add_u32 s14, s4, s1
	v_add_co_u32_e32 v2, vcc, s65, v2
	s_addc_u32 s15, s5, s15
	s_or_b32 s1, s0, 7
	v_addc_co_u32_e32 v3, vcc, 0, v3, vcc
	global_load_dwordx4 v[32:35], v[0:1], off
	global_load_dwordx4 v[36:39], v[2:3], off
	v_lshl_add_u64 v[0:1], s[14:15], 0, v[192:193]
	s_mul_hi_i32 s15, s1, 0x3800
	s_mulk_i32 s1, 0x3800
	s_add_u32 s14, s4, s1
	s_addc_u32 s15, s5, s15
	s_or_b32 s1, s0, 8
	v_add_co_u32_e32 v0, vcc, s65, v0
	v_lshl_add_u64 v[2:3], s[14:15], 0, v[192:193]
	s_mul_hi_i32 s15, s1, 0x3800
	s_mulk_i32 s1, 0x3800
	v_addc_co_u32_e32 v1, vcc, 0, v1, vcc
	s_add_u32 s14, s4, s1
	v_add_co_u32_e32 v2, vcc, s65, v2
	s_addc_u32 s15, s5, s15
	s_or_b32 s1, s0, 9
	v_addc_co_u32_e32 v3, vcc, 0, v3, vcc
	global_load_dwordx4 v[40:43], v[0:1], off
	global_load_dwordx4 v[44:47], v[2:3], off
	v_lshl_add_u64 v[0:1], s[14:15], 0, v[192:193]
	s_mul_hi_i32 s15, s1, 0x3800
	s_mulk_i32 s1, 0x3800
	s_add_u32 s14, s4, s1
	s_addc_u32 s15, s5, s15
	s_or_b32 s1, s0, 10
	v_add_co_u32_e32 v0, vcc, s65, v0
	v_lshl_add_u64 v[2:3], s[14:15], 0, v[192:193]
	s_mul_hi_i32 s15, s1, 0x3800
	s_mulk_i32 s1, 0x3800
	v_addc_co_u32_e32 v1, vcc, 0, v1, vcc
	s_add_u32 s14, s4, s1
	v_add_co_u32_e32 v2, vcc, s65, v2
	s_addc_u32 s15, s5, s15
	s_or_b32 s1, s0, 11
	v_addc_co_u32_e32 v3, vcc, 0, v3, vcc
	global_load_dwordx4 v[16:19], v[0:1], off
	global_load_dwordx4 v[20:23], v[2:3], off
	v_lshl_add_u64 v[0:1], s[14:15], 0, v[192:193]
	s_mul_hi_i32 s15, s1, 0x3800
	s_mulk_i32 s1, 0x3800
	s_add_u32 s14, s4, s1
	s_addc_u32 s15, s5, s15
	s_or_b32 s1, s0, 12
	v_add_co_u32_e32 v0, vcc, s65, v0
	v_lshl_add_u64 v[2:3], s[14:15], 0, v[192:193]
	s_mul_hi_i32 s15, s1, 0x3800
	s_mulk_i32 s1, 0x3800
	v_addc_co_u32_e32 v1, vcc, 0, v1, vcc
	s_add_u32 s14, s4, s1
	v_add_co_u32_e32 v2, vcc, s65, v2
	s_addc_u32 s15, s5, s15
	s_or_b32 s1, s0, 13
	v_addc_co_u32_e32 v3, vcc, 0, v3, vcc
	global_load_dwordx4 v[24:27], v[0:1], off
	global_load_dwordx4 v[28:31], v[2:3], off
	v_lshl_add_u64 v[0:1], s[14:15], 0, v[192:193]
	s_mul_hi_i32 s15, s1, 0x3800
	s_mulk_i32 s1, 0x3800
	s_add_u32 s14, s4, s1
	s_addc_u32 s15, s5, s15
	s_or_b32 s1, s0, 14
	v_lshl_add_u64 v[2:3], s[14:15], 0, v[192:193]
	s_mul_hi_i32 s15, s1, 0x3800
	s_mulk_i32 s1, 0x3800
	v_add_co_u32_e32 v0, vcc, s65, v0
	s_add_u32 s14, s4, s1
	s_nop 0
	v_addc_co_u32_e32 v1, vcc, 0, v1, vcc
	s_addc_u32 s15, s5, s15
	s_or_b32 s0, s0, 15
	v_add_co_u32_e32 v4, vcc, s65, v2
	s_mul_hi_i32 s1, s0, 0x3800
	s_mulk_i32 s0, 0x3800
	v_addc_co_u32_e32 v5, vcc, 0, v3, vcc
	v_lshl_add_u64 v[8:9], s[14:15], 0, v[192:193]
	s_add_u32 s0, s4, s0
	v_add_co_u32_e32 v8, vcc, s65, v8
	s_addc_u32 s1, s5, s1
	s_nop 0
	v_addc_co_u32_e32 v9, vcc, 0, v9, vcc
	v_lshl_add_u64 v[10:11], s[0:1], 0, v[192:193]
	v_add_co_u32_e32 v12, vcc, s65, v10
	global_load_dwordx4 v[0:3], v[0:1], off
	s_nop 0
	global_load_dwordx4 v[4:7], v[4:5], off
	v_addc_co_u32_e32 v13, vcc, 0, v11, vcc
	global_load_dwordx4 v[8:11], v[8:9], off
	s_nop 0
	global_load_dwordx4 v[12:15], v[12:13], off
	s_waitcnt vmcnt(0) lgkmcnt(0)
	v_lshlrev_b32_e32 v174, 16, v48
	v_lshlrev_b32_e32 v176, 16, v56
	v_lshlrev_b32_e32 v175, 16, v52
	v_add_f32_e32 v66, 0, v174
	v_add_f32_e32 v67, 0, v175
	v_add_f32_e32 v68, 0, v176
	v_and_b32_e32 v170, 0xffff0000, v48
	v_and_b32_e32 v172, 0xffff0000, v56
	v_and_b32_e32 v171, 0xffff0000, v52
	v_add_f32_e32 v48, v66, v170
	v_add_f32_e32 v52, v67, v171
	v_add_f32_e32 v56, v68, v172
	v_lshlrev_b32_e32 v166, 16, v49
	v_lshlrev_b32_e32 v168, 16, v57
	v_lshlrev_b32_e32 v167, 16, v53
	v_add_f32_e32 v48, v48, v166
	v_add_f32_e32 v52, v52, v167
	v_add_f32_e32 v56, v56, v168
	v_and_b32_e32 v162, 0xffff0000, v49
	v_and_b32_e32 v164, 0xffff0000, v57
	v_and_b32_e32 v163, 0xffff0000, v53
	v_add_f32_e32 v48, v48, v162
	v_add_f32_e32 v49, v52, v163
	v_add_f32_e32 v52, v56, v164
	v_lshlrev_b32_e32 v158, 16, v50
	v_lshlrev_b32_e32 v160, 16, v58
	v_lshlrev_b32_e32 v159, 16, v54
	v_add_f32_e32 v48, v48, v158
	v_add_f32_e32 v49, v49, v159
	v_add_f32_e32 v52, v52, v160
	v_and_b32_e32 v154, 0xffff0000, v50
	v_and_b32_e32 v156, 0xffff0000, v58
	v_and_b32_e32 v155, 0xffff0000, v54
	v_add_f32_e32 v48, v48, v154
	v_add_f32_e32 v49, v49, v155
	v_add_f32_e32 v50, v52, v156
	v_lshlrev_b32_e32 v146, 16, v51
	v_lshlrev_b32_e32 v148, 16, v59
	v_lshlrev_b32_e32 v147, 16, v55
	v_add_f32_e32 v48, v48, v146
	v_add_f32_e32 v49, v49, v147
	v_add_f32_e32 v50, v50, v148
	v_and_b32_e32 v150, 0xffff0000, v51
	v_and_b32_e32 v152, 0xffff0000, v59
	v_and_b32_e32 v151, 0xffff0000, v55
	v_lshlrev_b32_e32 v145, 16, v44
	v_lshlrev_b32_e32 v144, 16, v40
	v_lshlrev_b32_e32 v143, 16, v36
	v_lshlrev_b32_e32 v142, 16, v32
	v_add_f32_e32 v183, v48, v150
	v_add_f32_e32 v184, v49, v151
	v_add_f32_e32 v185, v50, v152
	v_add_f32_e32 v48, 0, v142
	v_add_f32_e32 v49, 0, v143
	v_add_f32_e32 v50, 0, v144
	v_add_f32_e32 v51, 0, v145
	v_and_b32_e32 v123, 0xffff0000, v44
	v_and_b32_e32 v122, 0xffff0000, v40
	v_and_b32_e32 v131, 0xffff0000, v36
	v_and_b32_e32 v130, 0xffff0000, v32
	v_add_f32_e32 v44, v48, v130
	v_add_f32_e32 v48, v49, v131
	v_add_f32_e32 v49, v50, v122
	v_add_f32_e32 v50, v51, v123
	v_lshlrev_b32_e32 v137, 16, v45
	v_lshlrev_b32_e32 v136, 16, v41
	v_lshlrev_b32_e32 v141, 16, v37
	v_lshlrev_b32_e32 v140, 16, v33
	v_add_f32_e32 v44, v44, v140
	v_add_f32_e32 v48, v48, v141
	v_add_f32_e32 v49, v49, v136
	v_add_f32_e32 v50, v50, v137
	v_and_b32_e32 v133, 0xffff0000, v45
	v_and_b32_e32 v132, 0xffff0000, v41
	v_and_b32_e32 v139, 0xffff0000, v37
	v_and_b32_e32 v138, 0xffff0000, v33
	v_add_f32_e32 v33, v44, v138
	v_add_f32_e32 v37, v48, v139
	v_add_f32_e32 v41, v49, v132
	v_add_f32_e32 v44, v50, v133
	v_lshlrev_b32_e32 v127, 16, v46
	v_lshlrev_b32_e32 v126, 16, v42
	v_lshlrev_b32_e32 v135, 16, v38
	v_add_f32_e32 v37, v37, v135
	v_add_f32_e32 v41, v41, v126
	v_add_f32_e32 v44, v44, v127
	v_and_b32_e32 v121, 0xffff0000, v46
	v_and_b32_e32 v120, 0xffff0000, v42
	v_and_b32_e32 v129, 0xffff0000, v38
	v_lshlrev_b32_e32 v134, 16, v34
	v_and_b32_e32 v128, 0xffff0000, v34
	v_add_f32_e32 v34, v37, v129
	v_add_f32_e32 v37, v41, v120
	v_add_f32_e32 v38, v44, v121
	v_lshlrev_b32_e32 v117, 16, v47
	v_lshlrev_b32_e32 v116, 16, v43
	v_add_f32_e32 v37, v37, v116
	v_add_f32_e32 v38, v38, v117
	v_and_b32_e32 v115, 0xffff0000, v47
	v_and_b32_e32 v114, 0xffff0000, v43
	v_lshlrev_b32_e32 v87, 16, v28
	v_lshlrev_b32_e32 v86, 16, v24
	v_lshlrev_b32_e32 v83, 16, v20
	v_lshlrev_b32_e32 v82, 16, v16
	v_lshlrev_b32_e32 v125, 16, v39
	v_lshlrev_b32_e32 v124, 16, v35
	v_and_b32_e32 v119, 0xffff0000, v39
	v_and_b32_e32 v118, 0xffff0000, v35
	v_add_f32_e32 v35, v37, v114
	v_add_f32_e32 v37, v38, v115
	v_add_f32_e32 v38, 0, v82
	v_add_f32_e32 v39, 0, v83
	v_add_f32_e32 v41, 0, v86
	v_add_f32_e32 v42, 0, v87
	v_and_b32_e32 v79, 0xffff0000, v28
	v_and_b32_e32 v78, 0xffff0000, v24
	v_and_b32_e32 v81, 0xffff0000, v20
	v_and_b32_e32 v80, 0xffff0000, v16
	v_add_f32_e32 v28, v38, v80
	v_add_f32_e32 v38, v39, v81
	v_add_f32_e32 v39, v41, v78
	v_add_f32_e32 v41, v42, v79
	v_lshlrev_b32_e32 v91, 16, v29
	v_lshlrev_b32_e32 v90, 16, v25
	v_lshlrev_b32_e32 v93, 16, v21
	v_lshlrev_b32_e32 v92, 16, v17
	v_add_f32_e32 v28, v28, v92
	v_add_f32_e32 v38, v38, v93
	v_add_f32_e32 v39, v39, v90
	v_add_f32_e32 v41, v41, v91
	v_and_b32_e32 v95, 0xffff0000, v29
	v_and_b32_e32 v94, 0xffff0000, v25
	v_and_b32_e32 v97, 0xffff0000, v21
	v_and_b32_e32 v96, 0xffff0000, v17
	v_add_f32_e32 v17, v28, v96
	v_add_f32_e32 v21, v38, v97
	v_add_f32_e32 v25, v39, v94
	v_add_f32_e32 v28, v41, v95
	v_lshlrev_b32_e32 v99, 16, v30
	v_lshlrev_b32_e32 v98, 16, v26
	v_lshlrev_b32_e32 v101, 16, v22
	v_lshlrev_b32_e32 v177, 16, v60
	v_add_f32_e32 v21, v21, v101
	v_add_f32_e32 v25, v25, v98
	v_add_f32_e32 v28, v28, v99
	v_and_b32_e32 v103, 0xffff0000, v30
	v_and_b32_e32 v102, 0xffff0000, v26
	v_and_b32_e32 v105, 0xffff0000, v22
	v_add_f32_e32 v69, 0, v177
	v_and_b32_e32 v173, 0xffff0000, v60
	v_lshlrev_b32_e32 v100, 16, v18
	v_and_b32_e32 v104, 0xffff0000, v18
	v_add_f32_e32 v18, v21, v105
	v_add_f32_e32 v21, v25, v102
	v_add_f32_e32 v22, v28, v103
	v_lshlrev_b32_e32 v107, 16, v31
	v_lshlrev_b32_e32 v106, 16, v27
	v_add_f32_e32 v60, v69, v173
	v_lshlrev_b32_e32 v169, 16, v61
	v_add_f32_e32 v21, v21, v106
	v_add_f32_e32 v22, v22, v107
	v_and_b32_e32 v111, 0xffff0000, v31
	v_and_b32_e32 v110, 0xffff0000, v27
	v_lshlrev_b32_e32 v88, 16, v8
	v_lshlrev_b32_e32 v85, 16, v4
	v_lshlrev_b32_e32 v84, 16, v0
	v_add_f32_e32 v60, v60, v169
	v_and_b32_e32 v165, 0xffff0000, v61
	v_lshlrev_b32_e32 v109, 16, v23
	v_lshlrev_b32_e32 v108, 16, v19
	v_and_b32_e32 v113, 0xffff0000, v23
	v_and_b32_e32 v112, 0xffff0000, v19
	v_add_f32_e32 v19, v21, v110
	v_add_f32_e32 v21, v22, v111
	v_add_f32_e32 v22, 0, v84
	v_add_f32_e32 v23, 0, v85
	v_add_f32_e32 v25, 0, v88
	v_and_b32_e32 v56, 0xffff0000, v8
	v_and_b32_e32 v67, 0xffff0000, v4
	v_and_b32_e32 v66, 0xffff0000, v0
	v_add_f32_e32 v53, v60, v165
	v_lshlrev_b32_e32 v161, 16, v62
	v_lshlrev_b32_e32 v89, 16, v12
	v_and_b32_e32 v57, 0xffff0000, v12
	v_add_f32_e32 v12, v22, v66
	v_add_f32_e32 v22, v23, v67
	v_add_f32_e32 v23, v25, v56
	v_lshlrev_b32_e32 v72, 16, v9
	v_lshlrev_b32_e32 v77, 16, v5
	v_add_f32_e32 v53, v53, v161
	v_and_b32_e32 v157, 0xffff0000, v62
	v_add_f32_e32 v22, v22, v77
	v_add_f32_e32 v23, v23, v72
	v_and_b32_e32 v68, 0xffff0000, v9
	v_and_b32_e32 v75, 0xffff0000, v5
	v_add_f32_e32 v52, v53, v157
	v_lshlrev_b32_e32 v149, 16, v63
	v_add_f32_e32 v5, v22, v75
	v_add_f32_e32 v9, v23, v68
	v_lshlrev_b32_e32 v60, 16, v10
	v_lshlrev_b32_e32 v71, 16, v6
	v_add_f32_e32 v52, v52, v149
	v_and_b32_e32 v153, 0xffff0000, v63
	v_add_f32_e32 v17, v17, v100
	v_add_f32_e32 v5, v5, v71
	v_add_f32_e32 v9, v9, v60
	v_and_b32_e32 v54, 0xffff0000, v10
	v_and_b32_e32 v63, 0xffff0000, v6
	v_add_f32_e32 v186, v52, v153
	v_add_f32_e32 v17, v17, v104
	v_lshlrev_b32_e32 v70, 16, v2
	v_and_b32_e32 v62, 0xffff0000, v2
	v_add_f32_e32 v2, v5, v63
	v_add_f32_e32 v5, v9, v54
	v_lshlrev_b32_e32 v52, 16, v11
	v_mul_f32_e32 v182, v170, v170
	v_mul_f32_e32 v16, v80, v80
	v_add_f32_e32 v17, v17, v108
	v_add_f32_e32 v5, v5, v52
	v_and_b32_e32 v48, 0xffff0000, v11
	v_cmp_lt_i32_e32 vcc, v224, v218
	v_fmac_f32_e32 v182, v174, v174
	v_fmac_f32_e32 v16, v82, v82
	v_add_f32_e32 v17, v17, v112
	v_lshlrev_b32_e32 v58, 16, v3
	v_and_b32_e32 v50, 0xffff0000, v3
	v_add_f32_e32 v3, v5, v48
	v_cndmask_b32_e32 v5, v217, v224, vcc
	v_cmp_gt_u32_e32 vcc, 32, v178
	v_mul_f32_e32 v181, v171, v171
	v_fmac_f32_e32 v182, v166, v166
	v_mul_f32_e32 v20, v81, v81
	v_fmac_f32_e32 v16, v92, v92
	v_lshlrev_b32_e32 v59, 16, v7
	v_and_b32_e32 v51, 0xffff0000, v7
	v_lshlrev_b32_e32 v5, 2, v5
	v_cndmask_b32_e32 v7, v183, v17, vcc
	v_fmac_f32_e32 v181, v175, v175
	v_fmac_f32_e32 v182, v162, v162
	v_fmac_f32_e32 v20, v83, v83
	v_fmac_f32_e32 v16, v96, v96
	ds_bpermute_b32 v7, v5, v7
	v_fmac_f32_e32 v181, v167, v167
	v_fmac_f32_e32 v182, v158, v158
	v_fmac_f32_e32 v20, v93, v93
	v_fmac_f32_e32 v16, v100, v100
	v_fmac_f32_e32 v181, v163, v163
	v_fmac_f32_e32 v182, v154, v154
	v_fmac_f32_e32 v20, v97, v97
	v_fmac_f32_e32 v16, v104, v104
	v_add_f32_e32 v26, 0, v89
	v_fmac_f32_e32 v181, v159, v159
	v_fmac_f32_e32 v182, v146, v146
	v_fmac_f32_e32 v20, v101, v101
	v_fmac_f32_e32 v16, v108, v108
	v_add_f32_e32 v25, v26, v57
	v_lshlrev_b32_e32 v73, 16, v13
	v_lshlrev_b32_e32 v76, 16, v1
	v_fmac_f32_e32 v181, v155, v155
	v_fmac_f32_e32 v182, v150, v150
	v_fmac_f32_e32 v20, v105, v105
	v_add_f32_e32 v18, v18, v109
	v_fmac_f32_e32 v16, v112, v112
	v_add_f32_e32 v12, v12, v76
	v_add_f32_e32 v25, v25, v73
	v_and_b32_e32 v69, 0xffff0000, v13
	v_and_b32_e32 v74, 0xffff0000, v1
	v_cndmask_b32_e32 v9, v17, v183, vcc
	v_fmac_f32_e32 v181, v147, v147
	v_fmac_f32_e32 v20, v109, v109
	v_add_f32_e32 v18, v18, v113
	v_add_f32_e32 v1, v12, v74
	v_add_f32_e32 v12, v25, v69
	v_lshlrev_b32_e32 v61, 16, v14
	s_waitcnt lgkmcnt(0)
	v_add_f32_e32 v7, v9, v7
	v_cndmask_b32_e32 v9, v182, v16, vcc
	v_mul_f32_e32 v179, v172, v172
	v_fmac_f32_e32 v181, v151, v151
	v_mul_f32_e32 v24, v78, v78
	v_fmac_f32_e32 v20, v113, v113
	v_add_f32_e32 v12, v12, v61
	v_and_b32_e32 v55, 0xffff0000, v14
	ds_bpermute_b32 v9, v5, v9
	v_cndmask_b32_e32 v11, v184, v18, vcc
	v_fmac_f32_e32 v179, v176, v176
	v_fmac_f32_e32 v24, v86, v86
	v_add_f32_e32 v6, v12, v55
	ds_bpermute_b32 v11, v5, v11
	v_cndmask_b32_e32 v12, v181, v20, vcc
	v_fmac_f32_e32 v179, v168, v168
	v_fmac_f32_e32 v24, v90, v90
	ds_bpermute_b32 v12, v5, v12
	v_fmac_f32_e32 v179, v164, v164
	v_fmac_f32_e32 v24, v94, v94
	v_fmac_f32_e32 v179, v160, v160
	v_fmac_f32_e32 v24, v98, v98
	v_cndmask_b32_e32 v10, v16, v182, vcc
	v_fmac_f32_e32 v179, v156, v156
	v_fmac_f32_e32 v24, v102, v102
	s_waitcnt lgkmcnt(2)
	v_add_f32_e32 v9, v10, v9
	v_cndmask_b32_e32 v10, v18, v184, vcc
	v_fmac_f32_e32 v179, v148, v148
	v_fmac_f32_e32 v24, v106, v106
	s_waitcnt lgkmcnt(1)
	v_add_f32_e32 v10, v10, v11
	v_cndmask_b32_e32 v11, v20, v181, vcc
	v_mul_f32_e32 v180, v173, v173
	v_fmac_f32_e32 v179, v152, v152
	v_mul_f32_e32 v42, v79, v79
	v_fmac_f32_e32 v24, v110, v110
	s_waitcnt lgkmcnt(0)
	v_add_f32_e32 v11, v11, v12
	v_cndmask_b32_e32 v12, v185, v19, vcc
	v_fmac_f32_e32 v180, v177, v177
	v_mul_f32_e32 v32, v130, v130
	v_fmac_f32_e32 v42, v87, v87
	v_mul_f32_e32 v0, v66, v66
	ds_bpermute_b32 v12, v5, v12
	v_cndmask_b32_e32 v14, v179, v24, vcc
	v_fmac_f32_e32 v180, v169, v169
	v_fmac_f32_e32 v32, v142, v142
	v_fmac_f32_e32 v42, v91, v91
	v_fmac_f32_e32 v0, v84, v84
	v_lshlrev_b32_e32 v53, 16, v15
	v_and_b32_e32 v49, 0xffff0000, v15
	ds_bpermute_b32 v14, v5, v14
	v_cndmask_b32_e32 v15, v186, v21, vcc
	v_fmac_f32_e32 v180, v165, v165
	v_fmac_f32_e32 v32, v140, v140
	v_fmac_f32_e32 v42, v95, v95
	v_fmac_f32_e32 v0, v76, v76
	ds_bpermute_b32 v15, v5, v15
	v_fmac_f32_e32 v180, v161, v161
	v_fmac_f32_e32 v32, v138, v138
	v_fmac_f32_e32 v42, v99, v99
	v_fmac_f32_e32 v0, v74, v74
	v_fmac_f32_e32 v180, v157, v157
	v_add_f32_e32 v33, v33, v134
	v_fmac_f32_e32 v32, v134, v134
	v_fmac_f32_e32 v42, v103, v103
	v_add_f32_e32 v1, v1, v70
	v_fmac_f32_e32 v0, v70, v70
	v_cndmask_b32_e32 v13, v19, v185, vcc
	v_fmac_f32_e32 v180, v149, v149
	v_add_f32_e32 v33, v33, v128
	v_fmac_f32_e32 v32, v128, v128
	v_fmac_f32_e32 v42, v107, v107
	v_add_f32_e32 v1, v1, v62
	v_fmac_f32_e32 v0, v62, v62
	s_waitcnt lgkmcnt(2)
	v_add_f32_e32 v12, v13, v12
	v_cndmask_b32_e32 v13, v24, v179, vcc
	v_fmac_f32_e32 v180, v153, v153
	v_mul_f32_e32 v36, v131, v131
	v_add_f32_e32 v33, v33, v124
	v_fmac_f32_e32 v32, v124, v124
	v_fmac_f32_e32 v42, v111, v111
	v_mul_f32_e32 v4, v67, v67
	v_add_f32_e32 v1, v1, v58
	v_fmac_f32_e32 v0, v58, v58
	s_waitcnt lgkmcnt(1)
	v_add_f32_e32 v13, v13, v14
	v_cndmask_b32_e32 v14, v21, v186, vcc
	v_fmac_f32_e32 v36, v143, v143
	v_add_f32_e32 v33, v33, v118
	v_fmac_f32_e32 v32, v118, v118
	v_fmac_f32_e32 v4, v85, v85
	v_add_f32_e32 v1, v1, v50
	v_fmac_f32_e32 v0, v50, v50
	s_waitcnt lgkmcnt(0)
	v_add_f32_e32 v14, v14, v15
	v_cndmask_b32_e32 v15, v180, v42, vcc
	v_fmac_f32_e32 v36, v141, v141
	v_fmac_f32_e32 v4, v77, v77
	ds_bpermute_b32 v15, v5, v15
	v_cndmask_b32_e32 v17, v33, v1, vcc
	v_cndmask_b32_e32 v18, v32, v0, vcc
	v_fmac_f32_e32 v36, v139, v139
	v_fmac_f32_e32 v4, v75, v75
	ds_bpermute_b32 v17, v5, v17
	ds_bpermute_b32 v18, v5, v18
	v_fmac_f32_e32 v36, v135, v135
	v_fmac_f32_e32 v4, v71, v71
	v_mul_f32_e32 v40, v122, v122
	v_fmac_f32_e32 v36, v129, v129
	v_add_f32_e32 v34, v34, v125
	v_mul_f32_e32 v8, v56, v56
	v_fmac_f32_e32 v4, v63, v63
	v_add_f32_e32 v2, v2, v59
	v_fmac_f32_e32 v40, v144, v144
	v_mul_f32_e32 v187, v123, v123
	v_fmac_f32_e32 v36, v125, v125
	v_add_f32_e32 v34, v34, v119
	v_fmac_f32_e32 v8, v88, v88
	v_mul_f32_e32 v26, v57, v57
	v_fmac_f32_e32 v4, v59, v59
	v_add_f32_e32 v2, v2, v51
	v_cndmask_b32_e32 v16, v42, v180, vcc
	v_fmac_f32_e32 v187, v145, v145
	v_fmac_f32_e32 v40, v136, v136
	v_fmac_f32_e32 v36, v119, v119
	v_fmac_f32_e32 v26, v89, v89
	v_fmac_f32_e32 v8, v72, v72
	v_fmac_f32_e32 v4, v51, v51
	s_waitcnt lgkmcnt(2)
	v_add_f32_e32 v15, v16, v15
	v_cndmask_b32_e32 v1, v1, v33, vcc
	v_cndmask_b32_e32 v0, v0, v32, vcc
	v_cndmask_b32_e32 v16, v34, v2, vcc
	v_fmac_f32_e32 v187, v137, v137
	v_fmac_f32_e32 v40, v132, v132
	v_fmac_f32_e32 v26, v73, v73
	v_fmac_f32_e32 v8, v68, v68
	s_waitcnt lgkmcnt(1)
	v_add_f32_e32 v1, v1, v17
	s_waitcnt lgkmcnt(0)
	v_add_f32_e32 v0, v0, v18
	ds_bpermute_b32 v16, v5, v16
	v_cndmask_b32_e32 v17, v36, v4, vcc
	v_cndmask_b32_e32 v18, v35, v3, vcc
	v_fmac_f32_e32 v187, v133, v133
	v_fmac_f32_e32 v40, v126, v126
	v_fmac_f32_e32 v26, v69, v69
	v_fmac_f32_e32 v8, v60, v60
	ds_bpermute_b32 v17, v5, v17
	ds_bpermute_b32 v18, v5, v18
	v_fmac_f32_e32 v187, v127, v127
	v_fmac_f32_e32 v40, v120, v120
	v_fmac_f32_e32 v26, v61, v61
	v_fmac_f32_e32 v8, v54, v54
	v_fmac_f32_e32 v187, v121, v121
	v_fmac_f32_e32 v40, v116, v116
	v_fmac_f32_e32 v26, v55, v55
	v_fmac_f32_e32 v8, v52, v52
	v_fmac_f32_e32 v187, v117, v117
	v_fmac_f32_e32 v40, v114, v114
	v_add_f32_e32 v6, v6, v53
	v_fmac_f32_e32 v26, v53, v53
	v_fmac_f32_e32 v8, v48, v48
	v_cndmask_b32_e32 v2, v2, v34, vcc
	v_fmac_f32_e32 v187, v115, v115
	v_add_f32_e32 v6, v6, v49
	v_fmac_f32_e32 v26, v49, v49
	s_waitcnt lgkmcnt(2)
	v_add_f32_e32 v2, v2, v16
	v_cndmask_b32_e32 v4, v4, v36, vcc
	v_cndmask_b32_e32 v3, v3, v35, vcc
	v_cndmask_b32_e32 v16, v40, v8, vcc
	s_waitcnt lgkmcnt(1)
	v_add_f32_e32 v4, v4, v17
	s_waitcnt lgkmcnt(0)
	v_add_f32_e32 v3, v3, v18
	ds_bpermute_b32 v16, v5, v16
	v_cndmask_b32_e32 v17, v37, v6, vcc
	v_cndmask_b32_e32 v18, v187, v26, vcc
	ds_bpermute_b32 v17, v5, v17
	ds_bpermute_b32 v5, v5, v18
	v_cndmask_b32_e32 v8, v8, v40, vcc
	s_waitcnt lgkmcnt(2)
	v_add_f32_e32 v8, v8, v16
	v_cndmask_b32_e32 v16, v26, v187, vcc
	v_cndmask_b32_e32 v6, v6, v37, vcc
	s_waitcnt lgkmcnt(0)
	v_add_f32_e32 v5, v16, v5
	v_and_b32_e32 v16, 16, v65
	v_cmp_lt_i32_e32 vcc, v223, v218
	v_add_f32_e32 v6, v6, v17
	v_cmp_lt_i32_e64 s[0:1], v222, v218
	v_cndmask_b32_e32 v17, v217, v223, vcc
	v_cmp_eq_u32_e32 vcc, 0, v16
	v_lshlrev_b32_e32 v17, 2, v17
	s_nop 0
	v_cndmask_b32_e32 v16, v7, v1, vcc
	v_cndmask_b32_e32 v1, v1, v7, vcc
	ds_bpermute_b32 v7, v17, v16
	v_cndmask_b32_e32 v16, v9, v0, vcc
	v_cndmask_b32_e32 v0, v0, v9, vcc
	v_cndmask_b32_e32 v9, v12, v3, vcc
	ds_bpermute_b32 v9, v17, v9
	s_waitcnt lgkmcnt(1)
	v_add_f32_e32 v1, v1, v7
	v_cndmask_b32_e32 v7, v11, v4, vcc
	ds_bpermute_b32 v7, v17, v7
	v_cndmask_b32_e32 v18, v10, v2, vcc
	v_cndmask_b32_e32 v2, v2, v10, vcc
	v_cndmask_b32_e32 v10, v13, v8, vcc
	v_cndmask_b32_e32 v4, v4, v11, vcc
	ds_bpermute_b32 v10, v17, v10
	v_cndmask_b32_e32 v3, v3, v12, vcc
	ds_bpermute_b32 v16, v17, v16
	s_waitcnt lgkmcnt(2)
	v_add_f32_e32 v4, v4, v7
	v_add_f32_e32 v3, v3, v9
	v_cndmask_b32_e32 v7, v8, v13, vcc
	v_cndmask_b32_e32 v8, v14, v6, vcc
	v_cndmask_b32_e32 v9, v15, v5, vcc
	ds_bpermute_b32 v18, v17, v18
	ds_bpermute_b32 v8, v17, v8
	ds_bpermute_b32 v9, v17, v9
	s_waitcnt lgkmcnt(4)
	v_add_f32_e32 v7, v7, v10
	v_and_b32_e32 v10, 8, v65
	s_waitcnt lgkmcnt(3)
	v_add_f32_e32 v0, v0, v16
	v_cndmask_b32_e32 v6, v6, v14, vcc
	v_cndmask_b32_e64 v11, v217, v222, s[0:1]
	v_cmp_eq_u32_e64 s[0:1], 0, v10
	v_cndmask_b32_e32 v5, v5, v15, vcc
	s_waitcnt lgkmcnt(2)
	v_add_f32_e32 v2, v2, v18
	v_lshlrev_b32_e32 v11, 2, v11
	v_cndmask_b32_e64 v10, v1, v3, s[0:1]
	s_waitcnt lgkmcnt(1)
	v_add_f32_e32 v6, v6, v8
	s_waitcnt lgkmcnt(0)
	v_add_f32_e32 v5, v5, v9
	v_cndmask_b32_e64 v1, v3, v1, s[0:1]
	v_cndmask_b32_e64 v3, v0, v7, s[0:1]
	v_cndmask_b32_e64 v0, v7, v0, s[0:1]
	ds_bpermute_b32 v3, v11, v3
	v_cndmask_b32_e64 v7, v2, v6, s[0:1]
	v_cndmask_b32_e64 v8, v4, v5, s[0:1]
	ds_bpermute_b32 v10, v11, v10
	ds_bpermute_b32 v7, v11, v7
	ds_bpermute_b32 v8, v11, v8
	s_waitcnt lgkmcnt(3)
	v_add_f32_e32 v0, v0, v3
	v_cndmask_b32_e64 v2, v6, v2, s[0:1]
	v_cndmask_b32_e64 v3, v5, v4, s[0:1]
	v_and_b32_e32 v4, 4, v65
	v_cmp_lt_i32_e32 vcc, v221, v218
	s_waitcnt lgkmcnt(2)
	v_add_f32_e32 v1, v1, v10
	s_waitcnt lgkmcnt(1)
	v_add_f32_e32 v2, v2, v7
	s_waitcnt lgkmcnt(0)
	v_add_f32_e32 v3, v3, v8
	v_cndmask_b32_e32 v5, v217, v221, vcc
	v_cmp_eq_u32_e32 vcc, 0, v4
	v_lshlrev_b32_e32 v5, 2, v5
	s_lshl_b32 s0, s13, 7
	v_cndmask_b32_e32 v4, v1, v2, vcc
	v_cndmask_b32_e32 v6, v0, v3, vcc
	ds_bpermute_b32 v4, v5, v4
	ds_bpermute_b32 v5, v5, v6
	v_cndmask_b32_e32 v1, v2, v1, vcc
	v_cndmask_b32_e32 v0, v3, v0, vcc
	v_and_b32_e32 v2, 2, v65
	v_cmp_lt_i32_e32 vcc, v220, v218
	s_waitcnt lgkmcnt(1)
	v_add_f32_e32 v1, v1, v4
	s_waitcnt lgkmcnt(0)
	v_add_f32_e32 v0, v0, v5
	v_cndmask_b32_e32 v3, v217, v220, vcc
	v_cmp_eq_u32_e32 vcc, 0, v2
	v_lshlrev_b32_e32 v3, 2, v3
	s_add_i32 s14, s0, 0
	v_cndmask_b32_e32 v2, v1, v0, vcc
	ds_bpermute_b32 v2, v3, v2
	v_cndmask_b32_e32 v0, v0, v1, vcc
	v_cmp_lt_i32_e32 vcc, v219, v218
	s_add_i32 s14, s14, 0x22400
	s_waitcnt lgkmcnt(0)
	v_add_f32_e32 v0, v0, v2
	v_cndmask_b32_e32 v1, v217, v219, vcc
	v_lshlrev_b32_e32 v1, 2, v1
	ds_bpermute_b32 v1, v1, v0
	v_and_b32_e32 v2, 1, v65
	v_cmp_eq_u32_e32 vcc, 0, v2
	s_and_saveexec_b64 s[0:1], vcc
	s_cbranch_execz .LBB0_124
	s_waitcnt lgkmcnt(0)
	v_add_f32_e32 v0, v0, v1
	v_lshl_add_u32 v1, v178, 1, s14
	ds_write_b32 v1, v0
